# v33 + attention row-sum chains split into two independent interleaved f32 accumulators (same add count, half the dependency depth)
# speedup vs baseline: 1.0249x; 1.0249x over previous
.LBB0_477:
	s_lshl_b32 s22, s22, 1
	v_add_u32_e32 v212, s22, v245
	ds_read_b64_tr_b16 v[208:209], v212 offset:24576
	ds_read_b64_tr_b16 v[210:211], v212 offset:25088
	v_mfma_f32_32x32x16_bf16 v[128:143], v[204:207], v[172:175], v[64:79]
	v_add_f32_e32 v112, v96, v98
	v_add_f32_e32 v113, v97, v99
	v_add_f32_e32 v112, v100, v112
	v_add_f32_e32 v113, v101, v113
	v_cvt_pk_bf16_f32 v156, v96, v97
	v_cvt_pk_bf16_f32 v157, v98, v99
	ds_read_b64_tr_b16 v[204:205], v212 offset:28672
	ds_read_b64_tr_b16 v[206:207], v212 offset:29184
	v_add_f32_e32 v96, v102, v112
	v_add_f32_e32 v97, v103, v113
	v_mfma_f32_32x32x16_bf16 v[112:127], v[196:199], v[172:175], v[64:79]
	v_add_f32_e32 v96, v104, v96
	v_add_f32_e32 v97, v105, v97
	v_cvt_pk_bf16_f32 v158, v100, v101
	v_cvt_pk_bf16_f32 v159, v102, v103
	ds_read_b64_tr_b16 v[100:101], v212 offset:25600
	ds_read_b64_tr_b16 v[102:103], v212 offset:26112
	v_mfma_f32_32x32x16_bf16 v[128:143], v[200:203], v[168:171], v[128:143]
	v_add_f32_e32 v96, v106, v96
	v_add_f32_e32 v97, v107, v97
	v_add_f32_e32 v144, v108, v96
	v_add_f32_e32 v145, v109, v97
	v_cvt_pk_bf16_f32 v152, v104, v105
	v_cvt_pk_bf16_f32 v153, v106, v107
	ds_read_b64_tr_b16 v[96:97], v212 offset:29696
	ds_read_b64_tr_b16 v[98:99], v212 offset:30208
	v_mfma_f32_32x32x16_bf16 v[112:127], v[192:195], v[168:171], v[112:127]
	v_add_f32_e32 v104, v110, v144
	v_add_f32_e32 v105, v111, v145
	v_add_f32_e32 v104, v80, v104
	v_add_f32_e32 v105, v81, v105
	v_cvt_pk_bf16_f32 v154, v108, v109
	v_cvt_pk_bf16_f32 v155, v110, v111
	ds_read_b64_tr_b16 v[108:109], v212 offset:26624
	ds_read_b64_tr_b16 v[110:111], v212 offset:27136
	v_mfma_f32_32x32x16_bf16 v[128:143], v[188:191], v[164:167], v[128:143]
	v_add_f32_e32 v104, v82, v104
	v_add_f32_e32 v105, v83, v105
	v_add_f32_e32 v144, v84, v104
	v_add_f32_e32 v145, v85, v105
	v_cvt_pk_bf16_f32 v148, v80, v81
	v_cvt_pk_bf16_f32 v149, v82, v83
	ds_read_b64_tr_b16 v[104:105], v212 offset:30720
	ds_read_b64_tr_b16 v[106:107], v212 offset:31232
	v_mfma_f32_32x32x16_bf16 v[112:127], v[184:187], v[164:167], v[112:127]
	v_add_f32_e32 v80, v86, v144
	v_add_f32_e32 v81, v87, v145
	v_add_f32_e32 v80, v88, v80
	v_add_f32_e32 v81, v89, v81
	v_cvt_pk_bf16_f32 v150, v84, v85
	v_cvt_pk_bf16_f32 v151, v86, v87
	ds_read_b64_tr_b16 v[84:85], v212 offset:27648
	ds_read_b64_tr_b16 v[86:87], v212 offset:28160
	v_mfma_f32_32x32x16_bf16 v[128:143], v[180:183], v[160:163], v[128:143]
	v_add_f32_e32 v80, v90, v80
	v_add_f32_e32 v81, v91, v81
	v_add_f32_e32 v80, v92, v80
	v_add_f32_e32 v81, v93, v81
	v_cvt_pk_bf16_f32 v144, v88, v89
	v_cvt_pk_bf16_f32 v145, v90, v91
	ds_read_b64_tr_b16 v[88:89], v212 offset:31744
	ds_read_b64_tr_b16 v[90:91], v212 offset:32256
	v_mfma_f32_32x32x16_bf16 v[112:127], v[176:179], v[160:163], v[112:127]
	v_add_f32_e32 v80, v94, v80
	v_add_f32_e32 v81, v95, v81
	v_add_f32_e32 v80, v80, v81
	v_cvt_pk_bf16_f32 v146, v92, v93
	v_cvt_pk_bf16_f32 v147, v94, v95
	s_waitcnt lgkmcnt(14)
	v_mfma_f32_32x32x16_bf16 v[0:15], v[156:159], v[208:211], v[0:15]
	v_max_f32_e32 v81, v129, v129
	v_max_f32_e32 v82, v128, v128
	v_max_f32_e32 v81, v82, v81
	s_nop 3
	v_max3_f32 v82, v130, v131, v113
	v_max3_f32 v81, v81, v112, v114
	v_max3_f32 v81, v81, v115, v132
	v_max3_f32 v82, v82, v134, v135
	s_waitcnt lgkmcnt(12)
	v_mfma_f32_32x32x16_bf16 v[48:63], v[156:159], v[204:207], v[48:63]
	s_add_u32 s37, s16, s24
	v_max3_f32 v81, v81, v133, v116
	v_max3_f32 v82, v82, v118, v119
	s_addc_u32 s39, s17, s19
	v_max3_f32 v81, v81, v117, v136
	v_max3_f32 v82, v82, v138, v139
	s_add_u32 s22, s37, 0x9b80800
	v_max3_f32 v81, v81, v137, v120
	v_max3_f32 v82, v82, v122, v123
	s_addc_u32 s23, s39, 0
	s_add_i32 s34, s33, s28
	s_mov_b32 m0, s34
	s_nop 0
	global_load_lds_dwordx4 v241, s[22:23]
	v_max3_f32 v81, v81, v121, v140
	v_max3_f32 v82, v82, v142, v143
	s_add_u32 s35, s20, s24
	v_max3_f32 v81, v81, v141, v124
	v_max3_f32 v82, v82, v126, v127
	s_addc_u32 s36, s21, s19
	v_add_f32_e32 v251, v251, v80
	v_max3_f32 v80, v81, v125, v82
	s_add_u32 s22, s35, 0x9ac1000
	v_mov_b32_e32 v81, v80
	s_addc_u32 s23, s36, 0
	s_lshl_b32 s34, s31, 1
	v_permlane32_swap_b32_e32 v80, v81
	s_add_i32 s34, s34, s29
	s_mov_b32 m0, s34
	s_nop 0
	global_load_lds_dwordx4 v242, s[22:23]
	s_add_u32 s22, s35, 0x9ac1080
	v_max_f32_e32 v80, v80, v81
	s_addc_u32 s23, s36, 0
	s_addk_i32 s34, 0x2000
	s_mov_b32 m0, s34
	s_nop 0
	global_load_lds_dwordx4 v242, s[22:23]
	v_cmp_lt_f32_e32 vcc, s25, v80
	s_cmp_lg_u64 vcc, 0
	s_cselect_b64 s[22:23], -1, 0
	s_cbranch_vccnz .LBB0_485

.LBB0_480:
	s_add_i32 s22, s31, 0x2000
	s_cmpk_lg_i32 s31, 0x4000
	s_cselect_b32 s34, s22, 0
	s_lshl_b32 s22, s33, 1
	v_add_u32_e32 v236, s22, v245
	ds_read_b64_tr_b16 v[212:213], v236 offset:24576
	ds_read_b64_tr_b16 v[214:215], v236 offset:25088
	v_mfma_f32_32x32x16_bf16 v[96:111], v[80:83], v[172:175], v[64:79]
	v_add_f32_e32 v84, v128, v130
	v_add_f32_e32 v85, v129, v131
	v_add_f32_e32 v84, v132, v84
	v_add_f32_e32 v85, v133, v85
	v_cvt_pk_bf16_f32 v156, v128, v129
	v_cvt_pk_bf16_f32 v157, v130, v131
	ds_read_b64_tr_b16 v[204:205], v236 offset:28672
	ds_read_b64_tr_b16 v[206:207], v236 offset:29184
	v_add_f32_e32 v128, v134, v84
	v_add_f32_e32 v129, v135, v85
	v_add_f32_e32 v128, v136, v128
	v_add_f32_e32 v129, v137, v129
	v_mfma_f32_32x32x16_bf16 v[80:95], v[196:199], v[172:175], v[64:79]
	v_cvt_pk_bf16_f32 v158, v132, v133
	v_cvt_pk_bf16_f32 v159, v134, v135
	ds_read_b64_tr_b16 v[208:209], v236 offset:25600
	ds_read_b64_tr_b16 v[210:211], v236 offset:26112
	v_mfma_f32_32x32x16_bf16 v[96:111], v[200:203], v[168:171], v[96:111]
	v_add_f32_e32 v128, v138, v128
	v_add_f32_e32 v129, v139, v129
	v_add_f32_e32 v128, v140, v128
	v_add_f32_e32 v129, v141, v129
	v_cvt_pk_bf16_f32 v152, v136, v137
	v_cvt_pk_bf16_f32 v153, v138, v139
	ds_read_b64_tr_b16 v[132:133], v236 offset:29696
	ds_read_b64_tr_b16 v[134:135], v236 offset:30208
	v_mfma_f32_32x32x16_bf16 v[80:95], v[192:195], v[168:171], v[80:95]
	v_add_f32_e32 v128, v142, v128
	v_add_f32_e32 v129, v143, v129
	v_add_f32_e32 v136, v112, v128
	v_add_f32_e32 v137, v113, v129
	v_cvt_pk_bf16_f32 v154, v140, v141
	v_cvt_pk_bf16_f32 v155, v142, v143
	ds_read_b64_tr_b16 v[128:129], v236 offset:26624
	ds_read_b64_tr_b16 v[130:131], v236 offset:27136
	v_mfma_f32_32x32x16_bf16 v[96:111], v[188:191], v[164:167], v[96:111]
	v_add_f32_e32 v136, v114, v136
	v_add_f32_e32 v137, v115, v137
	v_add_f32_e32 v136, v116, v136
	v_add_f32_e32 v137, v117, v137
	v_cvt_pk_bf16_f32 v148, v112, v113
	v_cvt_pk_bf16_f32 v149, v114, v115
	ds_read_b64_tr_b16 v[112:113], v236 offset:30720
	ds_read_b64_tr_b16 v[114:115], v236 offset:31232
	v_mfma_f32_32x32x16_bf16 v[80:95], v[184:187], v[164:167], v[80:95]
	v_add_f32_e32 v136, v118, v136
	v_add_f32_e32 v137, v119, v137
	v_add_f32_e32 v136, v120, v136
	v_add_f32_e32 v137, v121, v137
	v_cvt_pk_bf16_f32 v150, v116, v117
	v_cvt_pk_bf16_f32 v151, v118, v119
	ds_read_b64_tr_b16 v[116:117], v236 offset:27648
	ds_read_b64_tr_b16 v[118:119], v236 offset:28160
	v_mfma_f32_32x32x16_bf16 v[96:111], v[180:183], v[160:163], v[96:111]
	v_add_f32_e32 v136, v122, v136
	v_add_f32_e32 v137, v123, v137
	v_add_f32_e32 v136, v124, v136
	v_add_f32_e32 v137, v125, v137
	v_cvt_pk_bf16_f32 v144, v120, v121
	v_cvt_pk_bf16_f32 v145, v122, v123
	ds_read_b64_tr_b16 v[120:121], v236 offset:31744
	ds_read_b64_tr_b16 v[122:123], v236 offset:32256
	v_mfma_f32_32x32x16_bf16 v[80:95], v[176:179], v[160:163], v[80:95]
	v_add_f32_e32 v136, v126, v136
	v_add_f32_e32 v137, v127, v137
	v_add_f32_e32 v136, v136, v137
	v_cvt_pk_bf16_f32 v146, v124, v125
	v_cvt_pk_bf16_f32 v147, v126, v127
	s_waitcnt lgkmcnt(14)
	v_mfma_f32_32x32x16_bf16 v[0:15], v[156:159], v[212:215], v[0:15]
	v_max_f32_e32 v124, v97, v97
	v_max_f32_e32 v125, v96, v96
	v_max_f32_e32 v124, v125, v124
	s_nop 3
	v_max3_f32 v125, v98, v99, v81
	v_max3_f32 v124, v124, v80, v82
	v_max3_f32 v124, v124, v83, v100
	v_max3_f32 v125, v125, v102, v103
	s_waitcnt lgkmcnt(12)
	v_mfma_f32_32x32x16_bf16 v[48:63], v[156:159], v[204:207], v[48:63]
	v_max3_f32 v124, v124, v101, v84
	v_max3_f32 v125, v125, v86, v87
	v_max3_f32 v124, v124, v85, v104
	v_max3_f32 v125, v125, v106, v107
	v_max3_f32 v124, v124, v105, v88
	v_max3_f32 v125, v125, v90, v91
	v_max3_f32 v124, v124, v89, v108
	v_max3_f32 v125, v125, v110, v111
	s_add_u32 s22, s37, 0x9be0800
	v_max3_f32 v124, v124, v109, v92
	v_max3_f32 v125, v125, v94, v95
	s_addc_u32 s23, s39, 0
	s_add_i32 s33, s31, s28
	v_max3_f32 v124, v124, v93, v125
	s_mov_b32 m0, s33
	s_nop 0
	global_load_lds_dwordx4 v241, s[22:23]
	s_add_u32 s22, s35, 0x9b21000
	v_mov_b32_e32 v125, v124
	s_addc_u32 s23, s36, 0
	s_lshl_b32 s33, s34, 1
	v_permlane32_swap_b32_e32 v124, v125
	s_add_i32 s33, s33, s29
	s_mov_b32 m0, s33
	s_nop 0
	global_load_lds_dwordx4 v242, s[22:23]
	s_add_u32 s22, s35, 0x9b21080
	v_max_f32_e32 v124, v124, v125
	s_addc_u32 s23, s36, 0
	s_addk_i32 s33, 0x2000
	s_mov_b32 m0, s33
	s_nop 0
	global_load_lds_dwordx4 v242, s[22:23]
	v_cmp_lt_f32_e32 vcc, s25, v124
	s_cmp_lg_u64 vcc, 0
	v_add_f32_e32 v251, v251, v136
	s_cselect_b64 s[22:23], -1, 0
	s_cbranch_vccnz .LBB0_488

; #define WAIT_BAR(N) asm volatile("s_waitcnt vmcnt(" #N ") lgkmcnt(0)\n\ts_barrier" ::: "memory")
;   #define RESC() do { if constexpr (!NOMAX) if (resc) { asm volatile("s_waitcnt lgkmcnt(0)" ::: "memory"); \
;       _Pragma("unroll") for (int d_ = 0; d_ < 2 * DV2; ++d_) _Pragma("unroll") for (int r = 0; r < 16; ++r) o[d_][r] *= wsf[crow(r, hi)]; } } while (0)
;   #define ROT() do { sl_prev = sl_cur; sl_cur = sl_next; sl_next = (sl_next == (NSLOT - 1) * SLOTB) ? 0 : sl_next + SLOTB; } while (0)
;     ...
;   int t = 1;
;   for (; t + 5 < NT; t += 2) {
;     STEP(pB0, pB1, pA0, pA1, t, true, true, true);     if constexpr (DV2 == 2) { WAIT_BAR(3); } else { WAIT_BAR(2); } RESC(); ROT();
.LBB0_970:
	v_add_u32_e32 v65, s31, v189
	ds_read_b64_tr_b16 v[178:179], v65 offset:24576
	ds_read_b64_tr_b16 v[180:181], v65 offset:25088
	v_add_f32_e32 v86, v66, v68
	v_add_f32_e32 v87, v67, v69
	v_add_f32_e32 v86, v70, v86
	v_add_f32_e32 v87, v71, v87
	v_cvt_pk_bf16_f32 v142, v66, v67
	v_cvt_pk_bf16_f32 v143, v68, v69
	v_mfma_f32_32x32x16_bf16 v[98:113], v[82:85], v[158:161], v[32:47]
	ds_read_b64_tr_b16 v[174:175], v65 offset:28672
	ds_read_b64_tr_b16 v[176:177], v65 offset:29184
	v_add_f32_e32 v66, v72, v86
	v_add_f32_e32 v67, v73, v87
	v_mfma_f32_32x32x16_bf16 v[82:97], v[166:169], v[158:161], v[32:47]
	v_add_f32_e32 v130, v74, v66
	v_add_f32_e32 v131, v75, v67
	v_cvt_pk_bf16_f32 v144, v70, v71
	v_cvt_pk_bf16_f32 v145, v72, v73
	ds_read_b64_tr_b16 v[66:67], v65 offset:25600
	ds_read_b64_tr_b16 v[68:69], v65 offset:26112
	v_add_f32_e32 v70, v76, v130
	v_add_f32_e32 v71, v77, v131
	v_add_f32_e32 v130, v78, v70
	v_add_f32_e32 v131, v79, v71
	v_cvt_pk_bf16_f32 v138, v74, v75
	v_cvt_pk_bf16_f32 v139, v76, v77
	v_mfma_f32_32x32x16_bf16 v[98:113], v[170:173], v[154:157], v[98:113]
	ds_read_b64_tr_b16 v[70:71], v65 offset:29696
	ds_read_b64_tr_b16 v[72:73], v65 offset:30208
	v_mfma_f32_32x32x16_bf16 v[82:97], v[162:165], v[154:157], v[82:97]
	v_add_f32_e32 v74, v80, v130
	v_add_f32_e32 v75, v81, v131
	v_add_f32_e32 v130, v48, v74
	v_add_f32_e32 v131, v49, v75
	v_cvt_pk_bf16_f32 v140, v78, v79
	v_cvt_pk_bf16_f32 v141, v80, v81
	ds_read_b64_tr_b16 v[74:75], v65 offset:26624
	ds_read_b64_tr_b16 v[76:77], v65 offset:27136
	v_add_f32_e32 v78, v50, v130
	v_add_f32_e32 v79, v51, v131
	v_add_f32_e32 v78, v52, v78
	v_add_f32_e32 v79, v53, v79
	v_cvt_pk_bf16_f32 v134, v48, v49
	v_cvt_pk_bf16_f32 v135, v50, v51
	v_mfma_f32_32x32x16_bf16 v[98:113], v[126:129], v[150:153], v[98:113]
	ds_read_b64_tr_b16 v[48:49], v65 offset:30720
	ds_read_b64_tr_b16 v[50:51], v65 offset:31232
	v_mfma_f32_32x32x16_bf16 v[82:97], v[122:125], v[150:153], v[82:97]
	v_add_f32_e32 v78, v54, v78
	v_add_f32_e32 v79, v55, v79
	v_add_f32_e32 v78, v56, v78
	v_add_f32_e32 v79, v57, v79
	v_cvt_pk_bf16_f32 v136, v52, v53
	v_cvt_pk_bf16_f32 v137, v54, v55
	ds_read_b64_tr_b16 v[52:53], v65 offset:27648
	ds_read_b64_tr_b16 v[54:55], v65 offset:28160
	v_add_f32_e32 v78, v58, v78
	v_add_f32_e32 v79, v59, v79
	v_add_f32_e32 v78, v60, v78
	v_add_f32_e32 v79, v61, v79
	v_cvt_pk_bf16_f32 v130, v56, v57
	v_cvt_pk_bf16_f32 v131, v58, v59
	v_mfma_f32_32x32x16_bf16 v[98:113], v[118:121], v[146:149], v[98:113]
	ds_read_b64_tr_b16 v[56:57], v65 offset:31744
	ds_read_b64_tr_b16 v[58:59], v65 offset:32256
	v_mfma_f32_32x32x16_bf16 v[82:97], v[114:117], v[146:149], v[82:97]
	v_add_f32_e32 v78, v62, v78
	v_add_f32_e32 v79, v63, v79
	v_add_f32_e32 v65, v78, v79
	v_cvt_pk_bf16_f32 v132, v60, v61
	v_cvt_pk_bf16_f32 v133, v62, v63
	v_add_f32_e32 v64, v64, v65
	s_waitcnt lgkmcnt(14)
	v_mfma_f32_32x32x16_bf16 v[0:15], v[142:145], v[178:181], v[0:15]
	s_add_u32 s31, s16, s22
	s_addc_u32 s33, s17, 0
	s_add_i32 m0, s29, s18
	s_add_u32 s34, s31, 0x9ac0800
	s_addc_u32 s35, s33, 0
	global_load_lds_dwordx4 v184, s[34:35]
	v_exp_f32_e32 v98, v98
	v_exp_f32_e32 v99, v99
	v_exp_f32_e32 v100, v100
	v_exp_f32_e32 v101, v101
	s_waitcnt lgkmcnt(12)
	v_mfma_f32_32x32x16_bf16 v[16:31], v[142:145], v[174:177], v[16:31]
	s_add_u32 s34, s20, s22
	s_addc_u32 s35, s21, 0
	s_add_i32 m0, s28, s15
	s_add_u32 s36, s34, 0x9a60a00
	s_addc_u32 s37, s35, 0
	global_load_lds_dwordx4 v185, s[36:37]
	v_exp_f32_e32 v102, v102
	v_exp_f32_e32 v103, v103
	v_exp_f32_e32 v104, v104
	v_exp_f32_e32 v105, v105
	s_waitcnt lgkmcnt(0)
	v_add_u32_e32 v65, s28, v187
	ds_read_b128 v[60:63], v65
	ds_read_b128 v[118:121], v65 offset:512
	v_mfma_f32_32x32x16_bf16 v[0:15], v[138:141], v[66:69], v[0:15]
	v_exp_f32_e32 v106, v106
	v_exp_f32_e32 v107, v107
	v_exp_f32_e32 v108, v108
	v_exp_f32_e32 v109, v109
	ds_read_b128 v[122:125], v65 offset:2048
	ds_read_b128 v[126:129], v65 offset:2560
	v_mfma_f32_32x32x16_bf16 v[16:31], v[138:141], v[70:73], v[16:31]
	v_exp_f32_e32 v110, v110
	v_exp_f32_e32 v111, v111
	v_exp_f32_e32 v112, v112
	v_exp_f32_e32 v113, v113
	ds_read_b128 v[162:165], v65 offset:4096
	ds_read_b128 v[166:169], v65 offset:4608
	v_mfma_f32_32x32x16_bf16 v[0:15], v[134:137], v[74:77], v[0:15]
	v_exp_f32_e32 v82, v82
	v_exp_f32_e32 v83, v83
	v_exp_f32_e32 v84, v84
	v_exp_f32_e32 v85, v85
	ds_read_b128 v[170:173], v65 offset:6144
	ds_read_b128 v[114:117], v65 offset:6656
	v_mfma_f32_32x32x16_bf16 v[16:31], v[134:137], v[48:51], v[16:31]
	v_exp_f32_e32 v86, v86
	v_exp_f32_e32 v87, v87
	v_exp_f32_e32 v88, v88
	v_exp_f32_e32 v89, v89
	v_mfma_f32_32x32x16_bf16 v[0:15], v[130:133], v[52:55], v[0:15]
	v_exp_f32_e32 v90, v90
	v_exp_f32_e32 v91, v91
	v_exp_f32_e32 v92, v92
	v_exp_f32_e32 v93, v93
	v_mfma_f32_32x32x16_bf16 v[16:31], v[130:133], v[56:59], v[16:31]
	v_exp_f32_e32 v94, v94
	v_exp_f32_e32 v95, v95
	v_exp_f32_e32 v96, v96
	v_exp_f32_e32 v97, v97
	s_waitcnt vmcnt(2) lgkmcnt(0)
	s_barrier
; #define WAIT_BAR(N) asm volatile("s_waitcnt vmcnt(" #N ") lgkmcnt(0)\n\ts_barrier" ::: "memory")
;   #define RESC() do { if constexpr (!NOMAX) if (resc) { asm volatile("s_waitcnt lgkmcnt(0)" ::: "memory"); \
;       _Pragma("unroll") for (int d_ = 0; d_ < 2 * DV2; ++d_) _Pragma("unroll") for (int r = 0; r < 16; ++r) o[d_][r] *= wsf[crow(r, hi)]; } } while (0)
;   #define ROT() do { sl_prev = sl_cur; sl_cur = sl_next; sl_next = (sl_next == (NSLOT - 1) * SLOTB) ? 0 : sl_next + SLOTB; } while (0)
;     ...
;   int t = 1;
;   for (; t + 5 < NT; t += 2) {
;     STEP(pB0, pB1, pA0, pA1, t, true, true, true);     if constexpr (DV2 == 2) { WAIT_BAR(3); } else { WAIT_BAR(2); } RESC(); ROT();
;     STEP(pA0, pA1, pB0, pB1, t + 1, true, true, true); if constexpr (DV2 == 2) { WAIT_BAR(3); } else { WAIT_BAR(2); } RESC(); ROT();
	s_add_i32 s30, s28, 0x2000
	s_cmpk_lg_i32 s28, 0x4000
	s_cselect_b32 s30, s30, 0
	v_add_u32_e32 v65, s29, v189
	ds_read_b64_tr_b16 v[174:175], v65 offset:24576
	ds_read_b64_tr_b16 v[176:177], v65 offset:25088
	v_mfma_f32_32x32x16_bf16 v[66:81], v[60:63], v[158:161], v[32:47]
	v_add_f32_e32 v48, v98, v100
	v_add_f32_e32 v49, v99, v101
	v_add_f32_e32 v48, v102, v48
	v_add_f32_e32 v49, v103, v49
	v_cvt_pk_bf16_f32 v142, v98, v99
	v_cvt_pk_bf16_f32 v143, v100, v101
	ds_read_b64_tr_b16 v[178:179], v65 offset:28672
	ds_read_b64_tr_b16 v[180:181], v65 offset:29184
	v_add_f32_e32 v48, v104, v48
	v_add_f32_e32 v49, v105, v49
	v_add_f32_e32 v130, v106, v48
	v_add_f32_e32 v131, v107, v49
	v_mfma_f32_32x32x16_bf16 v[48:63], v[118:121], v[158:161], v[32:47]
	v_cvt_pk_bf16_f32 v144, v102, v103
	v_cvt_pk_bf16_f32 v145, v104, v105
	ds_read_b64_tr_b16 v[98:99], v65 offset:25600
	ds_read_b64_tr_b16 v[100:101], v65 offset:26112
	v_mfma_f32_32x32x16_bf16 v[66:81], v[122:125], v[154:157], v[66:81]
	v_add_f32_e32 v102, v108, v130
	v_add_f32_e32 v103, v109, v131
	v_add_f32_e32 v118, v110, v102
	v_add_f32_e32 v119, v111, v103
	v_cvt_pk_bf16_f32 v138, v106, v107
	v_cvt_pk_bf16_f32 v139, v108, v109
	ds_read_b64_tr_b16 v[102:103], v65 offset:29696
	ds_read_b64_tr_b16 v[104:105], v65 offset:30208
	v_mfma_f32_32x32x16_bf16 v[48:63], v[126:129], v[154:157], v[48:63]
	v_add_f32_e32 v106, v112, v118
	v_add_f32_e32 v107, v113, v119
	v_add_f32_e32 v118, v82, v106
	v_add_f32_e32 v119, v83, v107
	v_cvt_pk_bf16_f32 v140, v110, v111
	v_cvt_pk_bf16_f32 v141, v112, v113
	ds_read_b64_tr_b16 v[106:107], v65 offset:26624
	ds_read_b64_tr_b16 v[108:109], v65 offset:27136
	v_mfma_f32_32x32x16_bf16 v[66:81], v[162:165], v[150:153], v[66:81]
	v_add_f32_e32 v110, v84, v118
	v_add_f32_e32 v111, v85, v119
	v_add_f32_e32 v118, v86, v110
	v_add_f32_e32 v119, v87, v111
	v_cvt_pk_bf16_f32 v134, v82, v83
	v_cvt_pk_bf16_f32 v135, v84, v85
	ds_read_b64_tr_b16 v[110:111], v65 offset:30720
	ds_read_b64_tr_b16 v[112:113], v65 offset:31232
	v_mfma_f32_32x32x16_bf16 v[48:63], v[166:169], v[150:153], v[48:63]
	v_add_f32_e32 v82, v88, v118
	v_add_f32_e32 v83, v89, v119
	v_add_f32_e32 v82, v90, v82
	v_add_f32_e32 v83, v91, v83
	v_cvt_pk_bf16_f32 v136, v86, v87
	v_cvt_pk_bf16_f32 v137, v88, v89
	ds_read_b64_tr_b16 v[86:87], v65 offset:27648
	ds_read_b64_tr_b16 v[88:89], v65 offset:28160
	v_mfma_f32_32x32x16_bf16 v[66:81], v[170:173], v[146:149], v[66:81]
	v_add_f32_e32 v82, v92, v82
	v_add_f32_e32 v83, v93, v83
	v_add_f32_e32 v82, v94, v82
	v_add_f32_e32 v83, v95, v83
	v_cvt_pk_bf16_f32 v130, v90, v91
	v_cvt_pk_bf16_f32 v131, v92, v93
	ds_read_b64_tr_b16 v[90:91], v65 offset:31744
	ds_read_b64_tr_b16 v[92:93], v65 offset:32256
	v_mfma_f32_32x32x16_bf16 v[48:63], v[114:117], v[146:149], v[48:63]
	v_add_f32_e32 v82, v96, v82
	v_add_f32_e32 v83, v97, v83
	v_add_f32_e32 v65, v82, v83
	v_cvt_pk_bf16_f32 v132, v94, v95
	v_cvt_pk_bf16_f32 v133, v96, v97
	v_add_f32_e32 v64, v64, v65
	s_waitcnt lgkmcnt(14)
	v_mfma_f32_32x32x16_bf16 v[0:15], v[142:145], v[174:177], v[0:15]
	s_add_i32 m0, s28, s18
	s_add_u32 s36, s31, 0x9af0800
	s_addc_u32 s37, s33, 0
	global_load_lds_dwordx4 v184, s[36:37]
	v_exp_f32_e32 v66, v66
	v_exp_f32_e32 v67, v67
	v_exp_f32_e32 v68, v68
	v_exp_f32_e32 v69, v69
	s_waitcnt lgkmcnt(12)
	v_mfma_f32_32x32x16_bf16 v[16:31], v[142:145], v[178:181], v[16:31]
	s_add_i32 m0, s30, s15
	s_add_u32 s34, s34, 0x9a90a00
	s_addc_u32 s35, s35, 0
	global_load_lds_dwordx4 v185, s[34:35]
	v_exp_f32_e32 v70, v70
	v_exp_f32_e32 v71, v71
	v_exp_f32_e32 v72, v72
	v_exp_f32_e32 v73, v73
	v_add_u32_e32 v65, s30, v187
	ds_read_b128 v[82:85], v65
	ds_read_b128 v[166:169], v65 offset:512
	v_mfma_f32_32x32x16_bf16 v[0:15], v[138:141], v[98:101], v[0:15]
	v_exp_f32_e32 v74, v74
	s_waitcnt lgkmcnt(0)
	v_exp_f32_e32 v75, v75
	v_exp_f32_e32 v76, v76
	v_exp_f32_e32 v77, v77
	ds_read_b128 v[170:173], v65 offset:2048
	ds_read_b128 v[162:165], v65 offset:2560
	v_mfma_f32_32x32x16_bf16 v[16:31], v[138:141], v[102:105], v[16:31]
	v_exp_f32_e32 v78, v78
	v_exp_f32_e32 v79, v79
	v_exp_f32_e32 v80, v80
	v_exp_f32_e32 v81, v81
	ds_read_b128 v[126:129], v65 offset:4096
	ds_read_b128 v[122:125], v65 offset:4608
	v_mfma_f32_32x32x16_bf16 v[0:15], v[134:137], v[106:109], v[0:15]
	v_exp_f32_e32 v48, v48
	v_exp_f32_e32 v49, v49
	v_exp_f32_e32 v50, v50
	v_exp_f32_e32 v51, v51
	ds_read_b128 v[118:121], v65 offset:6144
	ds_read_b128 v[114:117], v65 offset:6656
	v_mfma_f32_32x32x16_bf16 v[16:31], v[134:137], v[110:113], v[16:31]
	v_exp_f32_e32 v52, v52
	v_exp_f32_e32 v53, v53
	v_exp_f32_e32 v54, v54
	v_exp_f32_e32 v55, v55
	v_mfma_f32_32x32x16_bf16 v[0:15], v[130:133], v[86:89], v[0:15]
	v_exp_f32_e32 v56, v56
	v_exp_f32_e32 v57, v57
	v_exp_f32_e32 v58, v58
	v_exp_f32_e32 v59, v59
	v_mfma_f32_32x32x16_bf16 v[16:31], v[130:133], v[90:93], v[16:31]
	v_exp_f32_e32 v60, v60
	v_exp_f32_e32 v61, v61
	v_exp_f32_e32 v62, v62
	v_exp_f32_e32 v63, v63
	s_add_i32 s33, s30, 0x2000
	s_cmpk_lg_i32 s30, 0x4000
	s_mov_b32 s31, s28
	s_cselect_b32 s28, s33, 0
	s_add_i32 s24, s24, 2
	s_add_u32 s20, s20, 0x60000
	s_addc_u32 s21, s21, 0
	s_waitcnt vmcnt(2) lgkmcnt(0)
	s_barrier
	s_add_u32 s16, s16, 0x60000
	s_addc_u32 s17, s17, 0
	s_mov_b32 s29, s30
	s_cmp_gt_u32 s24, 56
	s_cbranch_scc0 .LBB0_970
;   #define RESC() do { if constexpr (!NOMAX) if (resc) { asm volatile("s_waitcnt lgkmcnt(0)" ::: "memory"); \
;       _Pragma("unroll") for (int d_ = 0; d_ < 2 * DV2; ++d_) _Pragma("unroll") for (int r = 0; r < 16; ++r) o[d_][r] *= wsf[crow(r, hi)]; } } while (0)
;   #define ROT() do { sl_prev = sl_cur; sl_cur = sl_next; sl_next = (sl_next == (NSLOT - 1) * SLOTB) ? 0 : sl_next + SLOTB; } while (0)
;   #define ENDW(tt) do { if constexpr (DV2 == 2) { if ((tt) + 3 < NT) { WAIT_BAR(3); } else if ((tt) + 2 < NT) { WAIT_BAR(2); } else { WAIT_BAR(0); } } \
;     else { if ((tt) + 3 < NT) { WAIT_BAR(2); } else if ((tt) + 2 < NT) { WAIT_BAR(1); } else { WAIT_BAR(0); } } } while (0)
;     ...
;   for (; t + 1 < NT; t += 2) {
;     STEP(pB0, pB1, pA0, pA1, t, (t + 3 < NT), (t + 1 < NT), (t + 1 < NT));         ENDW(t);     RESC(); ROT();
;     STEP(pA0, pA1, pB0, pB1, t + 1, (t + 4 < NT), (t + 2 < NT), (t + 2 < NT));     ENDW(t + 1); RESC(); ROT();
	s_and_b32 s16, s23, 0x3fffffc0
	s_lshl_b32 s16, s16, 2
	s_add_i32 s16, s16, 0
	ds_read_b64_tr_b16 v[174:175], v189 offset:32768
	ds_read_b64_tr_b16 v[176:177], v189 offset:33280
	v_add_f32_e32 v65, v66, v67
	v_add_f32_e32 v65, v68, v65
	v_add_f32_e32 v65, v69, v65
	v_add_f32_e32 v65, v70, v65
	v_add_f32_e32 v65, v71, v65
	v_cvt_pk_bf16_f32 v142, v66, v67
	v_cvt_pk_bf16_f32 v143, v68, v69
	s_waitcnt lgkmcnt(9)
	v_mfma_f32_32x32x16_bf16 v[98:113], v[82:85], v[158:161], v[32:47]
	ds_read_b64_tr_b16 v[178:179], v189 offset:36864
	ds_read_b64_tr_b16 v[180:181], v189 offset:37376
	v_add_f32_e32 v65, v72, v65
	v_add_f32_e32 v65, v73, v65
	v_add_f32_e32 v65, v74, v65
	v_add_f32_e32 v65, v75, v65
	v_cvt_pk_bf16_f32 v144, v70, v71
	v_cvt_pk_bf16_f32 v145, v72, v73
	s_waitcnt lgkmcnt(10)
	v_mfma_f32_32x32x16_bf16 v[82:97], v[166:169], v[158:161], v[32:47]
	ds_read_b64_tr_b16 v[66:67], v189 offset:33792
	ds_read_b64_tr_b16 v[68:69], v189 offset:34304
	v_add_f32_e32 v65, v76, v65
	v_add_f32_e32 v65, v77, v65
	v_add_f32_e32 v65, v78, v65
	v_add_f32_e32 v65, v79, v65
	v_cvt_pk_bf16_f32 v138, v74, v75
	v_cvt_pk_bf16_f32 v139, v76, v77
	s_waitcnt lgkmcnt(11)
	v_mfma_f32_32x32x16_bf16 v[98:113], v[170:173], v[154:157], v[98:113]
	ds_read_b64_tr_b16 v[70:71], v189 offset:37888
	ds_read_b64_tr_b16 v[72:73], v189 offset:38400
	v_add_f32_e32 v65, v80, v65
	v_add_f32_e32 v65, v81, v65
	v_add_f32_e32 v65, v48, v65
	v_add_f32_e32 v65, v49, v65
	v_cvt_pk_bf16_f32 v140, v78, v79
	v_cvt_pk_bf16_f32 v141, v80, v81
	s_waitcnt lgkmcnt(12)
	v_mfma_f32_32x32x16_bf16 v[82:97], v[162:165], v[154:157], v[82:97]
	ds_read_b64_tr_b16 v[74:75], v189 offset:34816
	ds_read_b64_tr_b16 v[76:77], v189 offset:35328
	v_add_f32_e32 v65, v50, v65
	v_add_f32_e32 v65, v51, v65
	v_add_f32_e32 v65, v52, v65
	v_add_f32_e32 v65, v53, v65
	v_cvt_pk_bf16_f32 v134, v48, v49
	v_cvt_pk_bf16_f32 v135, v50, v51
	s_waitcnt lgkmcnt(13)
	v_mfma_f32_32x32x16_bf16 v[98:113], v[126:129], v[150:153], v[98:113]
	ds_read_b64_tr_b16 v[48:49], v189 offset:38912
	ds_read_b64_tr_b16 v[50:51], v189 offset:39424
	v_add_f32_e32 v65, v54, v65
	v_add_f32_e32 v65, v55, v65
	v_add_f32_e32 v65, v56, v65
	v_add_f32_e32 v65, v57, v65
	v_cvt_pk_bf16_f32 v136, v52, v53
	v_cvt_pk_bf16_f32 v137, v54, v55
	s_waitcnt lgkmcnt(14)
	v_mfma_f32_32x32x16_bf16 v[82:97], v[122:125], v[150:153], v[82:97]
	ds_read_b64_tr_b16 v[52:53], v189 offset:35840
	ds_read_b64_tr_b16 v[54:55], v189 offset:36352
	v_add_f32_e32 v65, v58, v65
	v_add_f32_e32 v65, v59, v65
	v_add_f32_e32 v65, v60, v65
	v_add_f32_e32 v65, v61, v65
	v_cvt_pk_bf16_f32 v130, v56, v57
	v_cvt_pk_bf16_f32 v131, v58, v59
	s_waitcnt lgkmcnt(14)
	v_mfma_f32_32x32x16_bf16 v[98:113], v[118:121], v[146:149], v[98:113]
	ds_read_b64_tr_b16 v[56:57], v189 offset:39936
	ds_read_b64_tr_b16 v[58:59], v189 offset:40448
	v_add_f32_e32 v65, v62, v65
	v_add_f32_e32 v65, v63, v65
	v_add_f32_e32 v65, 0, v65
	v_cvt_pk_bf16_f32 v132, v60, v61
	v_cvt_pk_bf16_f32 v133, v62, v63
	v_mfma_f32_32x32x16_bf16 v[82:97], v[114:117], v[146:149], v[82:97]
	s_add_u32 s20, s10, 0xba0000
	s_addc_u32 s21, s11, 0
	s_cmp_lg_u32 0, -1
	s_cselect_b32 s17, 0, 0
	s_add_i32 s17, s17, s19
	s_add_i32 s19, s17, 0x4000
	s_mov_b32 s22, m0
	s_mov_b32 m0, s19
	s_nop 0
	global_load_lds_dwordx4 v184, s[20:21]
	s_mov_b32 m0, s22
	s_add_u32 s20, s8, 0xb40000
	s_addc_u32 s21, s9, 0
	s_mov_b32 s19, m0
	s_mov_b32 m0, s15
	s_nop 0
	global_load_lds_dwordx4 v185, s[20:21]
	s_mov_b32 m0, s19
	v_add_f32_e32 v183, v64, v65
	s_waitcnt lgkmcnt(14)
	v_mfma_f32_32x32x16_bf16 v[0:15], v[142:145], v[174:177], v[0:15]
	v_exp_f32_e32 v98, v98
	v_exp_f32_e32 v99, v99
	v_exp_f32_e32 v100, v100
	v_exp_f32_e32 v101, v101
	s_waitcnt lgkmcnt(12)
	v_mfma_f32_32x32x16_bf16 v[16:31], v[142:145], v[178:181], v[16:31]
	v_exp_f32_e32 v102, v102
	v_exp_f32_e32 v103, v103
	v_exp_f32_e32 v104, v104
	v_exp_f32_e32 v105, v105
	ds_read_b128 v[60:63], v187
	ds_read_b128 v[78:81], v187 offset:512
	s_waitcnt lgkmcnt(12)
	v_mfma_f32_32x32x16_bf16 v[0:15], v[138:141], v[66:69], v[0:15]
	v_exp_f32_e32 v106, v106
	v_exp_f32_e32 v107, v107
	v_exp_f32_e32 v108, v108
	v_exp_f32_e32 v109, v109
	ds_read_b128 v[162:165], v187 offset:2048
	ds_read_b128 v[166:169], v187 offset:2560
	s_waitcnt lgkmcnt(12)
	v_mfma_f32_32x32x16_bf16 v[16:31], v[138:141], v[70:73], v[16:31]
	v_exp_f32_e32 v110, v110
	v_exp_f32_e32 v111, v111
	v_exp_f32_e32 v112, v112
	v_exp_f32_e32 v113, v113
	ds_read_b128 v[68:71], v187 offset:4096
	ds_read_b128 v[170:173], v187 offset:4608
	s_waitcnt lgkmcnt(12)
	v_mfma_f32_32x32x16_bf16 v[0:15], v[134:137], v[74:77], v[0:15]
	v_exp_f32_e32 v82, v82
	v_exp_f32_e32 v83, v83
	v_exp_f32_e32 v84, v84
	v_exp_f32_e32 v85, v85
	ds_read_b128 v[72:75], v187 offset:6144
	ds_read_b128 v[64:67], v187 offset:6656
	s_waitcnt lgkmcnt(12)
	v_mfma_f32_32x32x16_bf16 v[16:31], v[134:137], v[48:51], v[16:31]
	v_exp_f32_e32 v86, v86
	v_exp_f32_e32 v87, v87
	v_exp_f32_e32 v88, v88
	v_exp_f32_e32 v89, v89
	s_waitcnt lgkmcnt(10)
	v_mfma_f32_32x32x16_bf16 v[0:15], v[130:133], v[52:55], v[0:15]
	v_exp_f32_e32 v90, v90
	v_exp_f32_e32 v91, v91
	v_exp_f32_e32 v92, v92
	v_exp_f32_e32 v93, v93
	s_waitcnt lgkmcnt(8)
	v_mfma_f32_32x32x16_bf16 v[16:31], v[130:133], v[56:59], v[16:31]
	v_exp_f32_e32 v94, v94
	v_exp_f32_e32 v95, v95
	v_exp_f32_e32 v96, v96
	v_exp_f32_e32 v97, v97
	s_waitcnt vmcnt(2) lgkmcnt(0)
	s_barrier
;   #define RESC() do { if constexpr (!NOMAX) if (resc) { asm volatile("s_waitcnt lgkmcnt(0)" ::: "memory"); \
;       _Pragma("unroll") for (int d_ = 0; d_ < 2 * DV2; ++d_) _Pragma("unroll") for (int r = 0; r < 16; ++r) o[d_][r] *= wsf[crow(r, hi)]; } } while (0)
;   #define ROT() do { sl_prev = sl_cur; sl_cur = sl_next; sl_next = (sl_next == (NSLOT - 1) * SLOTB) ? 0 : sl_next + SLOTB; } while (0)
;   #define ENDW(tt) do { if constexpr (DV2 == 2) { if ((tt) + 3 < NT) { WAIT_BAR(3); } else if ((tt) + 2 < NT) { WAIT_BAR(2); } else { WAIT_BAR(0); } } \
;     else { if ((tt) + 3 < NT) { WAIT_BAR(2); } else if ((tt) + 2 < NT) { WAIT_BAR(1); } else { WAIT_BAR(0); } } } while (0)
;     ...
;   for (; t + 1 < NT; t += 2) {
;     STEP(pB0, pB1, pA0, pA1, t, (t + 3 < NT), (t + 1 < NT), (t + 1 < NT));         ENDW(t);     RESC(); ROT();
;     STEP(pA0, pA1, pB0, pB1, t + 1, (t + 4 < NT), (t + 2 < NT), (t + 2 < NT));     ENDW(t + 1); RESC(); ROT();
	ds_read_b64_tr_b16 v[174:175], v189 offset:40960
	ds_read_b64_tr_b16 v[176:177], v189 offset:41472
	v_add_f32_e32 v48, v98, v99
	v_add_f32_e32 v48, v100, v48
	v_add_f32_e32 v48, v101, v48
	v_add_f32_e32 v48, v102, v48
	v_add_f32_e32 v48, v103, v48
	v_cvt_pk_bf16_f32 v142, v98, v99
	v_cvt_pk_bf16_f32 v143, v100, v101
	s_waitcnt lgkmcnt(9)
	v_mfma_f32_32x32x16_bf16 v[114:129], v[60:63], v[158:161], v[32:47]
	ds_read_b64_tr_b16 v[98:99], v189 offset:45056
	ds_read_b64_tr_b16 v[100:101], v189 offset:45568
	v_add_f32_e32 v48, v104, v48
	v_add_f32_e32 v48, v105, v48
	v_add_f32_e32 v48, v106, v48
	v_add_f32_e32 v130, v107, v48
	s_waitcnt lgkmcnt(10)
	v_mfma_f32_32x32x16_bf16 v[48:63], v[78:81], v[158:161], v[32:47]
	v_cvt_pk_bf16_f32 v144, v102, v103
	v_cvt_pk_bf16_f32 v145, v104, v105
	ds_read_b64_tr_b16 v[76:77], v189 offset:41984
	ds_read_b64_tr_b16 v[78:79], v189 offset:42496
	v_add_f32_e32 v80, v108, v130
	v_add_f32_e32 v80, v109, v80
	v_add_f32_e32 v80, v110, v80
	v_add_f32_e32 v80, v111, v80
	v_cvt_pk_bf16_f32 v138, v106, v107
	v_cvt_pk_bf16_f32 v139, v108, v109
	s_waitcnt lgkmcnt(11)
	v_mfma_f32_32x32x16_bf16 v[114:129], v[162:165], v[154:157], v[114:129]
	ds_read_b64_tr_b16 v[102:103], v189 offset:46080
	ds_read_b64_tr_b16 v[104:105], v189 offset:46592
	s_waitcnt lgkmcnt(12)
	v_mfma_f32_32x32x16_bf16 v[48:63], v[166:169], v[154:157], v[48:63]
	v_add_f32_e32 v80, v112, v80
	v_add_f32_e32 v80, v113, v80
	v_add_f32_e32 v80, v82, v80
	v_add_f32_e32 v80, v83, v80
	v_cvt_pk_bf16_f32 v140, v110, v111
	v_cvt_pk_bf16_f32 v141, v112, v113
	ds_read_b64_tr_b16 v[106:107], v189 offset:43008
	ds_read_b64_tr_b16 v[108:109], v189 offset:43520
	s_waitcnt lgkmcnt(13)
	v_mfma_f32_32x32x16_bf16 v[114:129], v[68:71], v[150:153], v[114:129]
	v_add_f32_e32 v68, v84, v80
	v_add_f32_e32 v68, v85, v68
	v_add_f32_e32 v68, v86, v68
	v_add_f32_e32 v80, v87, v68
	v_cvt_pk_bf16_f32 v134, v82, v83
	v_cvt_pk_bf16_f32 v135, v84, v85
	ds_read_b64_tr_b16 v[68:69], v189 offset:47104
	ds_read_b64_tr_b16 v[70:71], v189 offset:47616
	s_waitcnt lgkmcnt(14)
	v_mfma_f32_32x32x16_bf16 v[48:63], v[170:173], v[150:153], v[48:63]
	v_add_f32_e32 v80, v88, v80
	v_add_f32_e32 v80, v89, v80
	v_add_f32_e32 v80, v90, v80
	v_add_f32_e32 v80, v91, v80
	v_cvt_pk_bf16_f32 v136, v86, v87
	v_cvt_pk_bf16_f32 v137, v88, v89
	ds_read_b64_tr_b16 v[84:85], v189 offset:44032
	ds_read_b64_tr_b16 v[86:87], v189 offset:44544
	s_waitcnt lgkmcnt(14)
	v_mfma_f32_32x32x16_bf16 v[114:129], v[72:75], v[146:149], v[114:129]
	v_add_f32_e32 v72, v92, v80
	v_add_f32_e32 v72, v93, v72
	v_add_f32_e32 v72, v94, v72
	v_add_f32_e32 v80, v95, v72
	v_cvt_pk_bf16_f32 v130, v90, v91
	v_cvt_pk_bf16_f32 v131, v92, v93
	ds_read_b64_tr_b16 v[72:73], v189 offset:48128
	ds_read_b64_tr_b16 v[74:75], v189 offset:48640
	v_mfma_f32_32x32x16_bf16 v[48:63], v[64:67], v[146:149], v[48:63]
	v_add_f32_e32 v64, v96, v80
	v_add_f32_e32 v64, v97, v64
	v_add_f32_e32 v64, 0, v64
	v_cvt_pk_bf16_f32 v132, v94, v95
	v_cvt_pk_bf16_f32 v133, v96, v97
	s_add_u32 s10, s10, 0xbd0000
	s_addc_u32 s11, s11, 0
	s_mov_b32 s19, m0
	s_mov_b32 m0, s18
	s_nop 0
	global_load_lds_dwordx4 v184, s[10:11]
	s_mov_b32 m0, s19
	s_add_u32 s10, s8, 0xb70000
	s_addc_u32 s11, s9, 0
	s_add_i32 s18, s17, 0x8000
	s_mov_b32 s19, m0
	s_mov_b32 m0, s18
	s_nop 0
	global_load_lds_dwordx4 v185, s[10:11]
	s_mov_b32 m0, s19
	v_add_f32_e32 v178, v183, v64
	s_waitcnt lgkmcnt(14)
	v_mfma_f32_32x32x16_bf16 v[0:15], v[142:145], v[174:177], v[0:15]
	v_exp_f32_e32 v114, v114
	v_exp_f32_e32 v115, v115
	v_exp_f32_e32 v116, v116
	v_exp_f32_e32 v117, v117
	s_waitcnt lgkmcnt(12)
	v_mfma_f32_32x32x16_bf16 v[16:31], v[142:145], v[98:101], v[16:31]
	v_exp_f32_e32 v118, v118
	v_exp_f32_e32 v119, v119
	v_exp_f32_e32 v120, v120
	v_exp_f32_e32 v121, v121
	ds_read_b128 v[64:67], v187 offset:8192
	ds_read_b128 v[88:91], v187 offset:8704
	s_waitcnt lgkmcnt(12)
	v_mfma_f32_32x32x16_bf16 v[0:15], v[138:141], v[76:79], v[0:15]
	v_exp_f32_e32 v122, v122
	v_exp_f32_e32 v123, v123
	v_exp_f32_e32 v124, v124
	v_exp_f32_e32 v125, v125
	ds_read_b128 v[92:95], v187 offset:10240
	ds_read_b128 v[162:165], v187 offset:10752
	s_waitcnt lgkmcnt(12)
	v_mfma_f32_32x32x16_bf16 v[16:31], v[138:141], v[102:105], v[16:31]
	v_exp_f32_e32 v126, v126
	v_exp_f32_e32 v127, v127
	v_exp_f32_e32 v128, v128
	v_exp_f32_e32 v129, v129
	ds_read_b128 v[166:169], v187 offset:12288
	ds_read_b128 v[170:173], v187 offset:12800
	s_waitcnt lgkmcnt(12)
	v_mfma_f32_32x32x16_bf16 v[0:15], v[134:137], v[106:109], v[0:15]
	v_exp_f32_e32 v48, v48
	v_exp_f32_e32 v49, v49
	v_exp_f32_e32 v50, v50
	v_exp_f32_e32 v51, v51
	ds_read_b128 v[174:177], v187 offset:14336
	ds_read_b128 v[80:83], v187 offset:14848
	s_waitcnt lgkmcnt(12)
	v_mfma_f32_32x32x16_bf16 v[16:31], v[134:137], v[68:71], v[16:31]
	v_exp_f32_e32 v52, v52
	v_exp_f32_e32 v53, v53
	v_exp_f32_e32 v54, v54
	v_exp_f32_e32 v55, v55
	s_waitcnt lgkmcnt(10)
	v_mfma_f32_32x32x16_bf16 v[0:15], v[130:133], v[84:87], v[0:15]
	v_exp_f32_e32 v56, v56
	v_exp_f32_e32 v57, v57
	v_exp_f32_e32 v58, v58
	v_exp_f32_e32 v59, v59
	s_waitcnt lgkmcnt(8)
	v_mfma_f32_32x32x16_bf16 v[16:31], v[130:133], v[72:75], v[16:31]
	v_exp_f32_e32 v60, v60
	v_exp_f32_e32 v61, v61
	v_exp_f32_e32 v62, v62
	v_exp_f32_e32 v63, v63
	s_waitcnt vmcnt(2) lgkmcnt(0)
	s_barrier
;   #define RESC() do { if constexpr (!NOMAX) if (resc) { asm volatile("s_waitcnt lgkmcnt(0)" ::: "memory"); \
;       _Pragma("unroll") for (int d_ = 0; d_ < 2 * DV2; ++d_) _Pragma("unroll") for (int r = 0; r < 16; ++r) o[d_][r] *= wsf[crow(r, hi)]; } } while (0)
;   #define ROT() do { sl_prev = sl_cur; sl_cur = sl_next; sl_next = (sl_next == (NSLOT - 1) * SLOTB) ? 0 : sl_next + SLOTB; } while (0)
;   #define ENDW(tt) do { if constexpr (DV2 == 2) { if ((tt) + 3 < NT) { WAIT_BAR(3); } else if ((tt) + 2 < NT) { WAIT_BAR(2); } else { WAIT_BAR(0); } } \
;     else { if ((tt) + 3 < NT) { WAIT_BAR(2); } else if ((tt) + 2 < NT) { WAIT_BAR(1); } else { WAIT_BAR(0); } } } while (0)
;     ...
;   for (; t + 1 < NT; t += 2) {
;     STEP(pB0, pB1, pA0, pA1, t, (t + 3 < NT), (t + 1 < NT), (t + 1 < NT));         ENDW(t);     RESC(); ROT();
;     STEP(pA0, pA1, pB0, pB1, t + 1, (t + 4 < NT), (t + 2 < NT), (t + 2 < NT));     ENDW(t + 1); RESC(); ROT();
	ds_read_b64_tr_b16 v[84:85], v189 offset:24576
	ds_read_b64_tr_b16 v[86:87], v189 offset:25088
	v_add_f32_e32 v68, v114, v115
	v_add_f32_e32 v68, v116, v68
	v_add_f32_e32 v68, v117, v68
	v_add_f32_e32 v68, v118, v68
	v_add_f32_e32 v68, v119, v68
	v_cvt_pk_bf16_f32 v142, v114, v115
	v_cvt_pk_bf16_f32 v143, v116, v117
	s_waitcnt lgkmcnt(9)
	v_mfma_f32_32x32x16_bf16 v[96:111], v[64:67], v[158:161], v[32:47]
	ds_read_b64_tr_b16 v[112:113], v189 offset:28672
	ds_read_b64_tr_b16 v[114:115], v189 offset:29184
	v_add_f32_e32 v64, v120, v68
	v_add_f32_e32 v64, v121, v64
	v_add_f32_e32 v64, v122, v64
	v_add_f32_e32 v116, v123, v64
	v_cvt_pk_bf16_f32 v144, v118, v119
	v_cvt_pk_bf16_f32 v145, v120, v121
	s_waitcnt lgkmcnt(10)
	v_mfma_f32_32x32x16_bf16 v[64:79], v[88:91], v[158:161], v[32:47]
	ds_read_b64_tr_b16 v[88:89], v189 offset:25600
	ds_read_b64_tr_b16 v[90:91], v189 offset:26112
	s_waitcnt lgkmcnt(11)
	v_mfma_f32_32x32x16_bf16 v[96:111], v[92:95], v[154:157], v[96:111]
	v_add_f32_e32 v92, v124, v116
	v_add_f32_e32 v92, v125, v92
	v_add_f32_e32 v92, v126, v92
	v_add_f32_e32 v116, v127, v92
	v_cvt_pk_bf16_f32 v138, v122, v123
	v_cvt_pk_bf16_f32 v139, v124, v125
	ds_read_b64_tr_b16 v[92:93], v189 offset:29696
	ds_read_b64_tr_b16 v[94:95], v189 offset:30208
	v_add_f32_e32 v116, v128, v116
	v_add_f32_e32 v116, v129, v116
	v_add_f32_e32 v116, v48, v116
	v_add_f32_e32 v120, v49, v116
	v_cvt_pk_bf16_f32 v140, v126, v127
	v_cvt_pk_bf16_f32 v141, v128, v129
	s_waitcnt lgkmcnt(12)
	v_mfma_f32_32x32x16_bf16 v[64:79], v[162:165], v[154:157], v[64:79]
	ds_read_b64_tr_b16 v[116:117], v189 offset:26624
	ds_read_b64_tr_b16 v[118:119], v189 offset:27136
	v_add_f32_e32 v120, v50, v120
	v_add_f32_e32 v120, v51, v120
	v_add_f32_e32 v120, v52, v120
	v_add_f32_e32 v120, v53, v120
	v_cvt_pk_bf16_f32 v134, v48, v49
	v_cvt_pk_bf16_f32 v135, v50, v51
	s_waitcnt lgkmcnt(13)
	v_mfma_f32_32x32x16_bf16 v[96:111], v[166:169], v[150:153], v[96:111]
	ds_read_b64_tr_b16 v[48:49], v189 offset:30720
	ds_read_b64_tr_b16 v[50:51], v189 offset:31232
	v_add_f32_e32 v120, v54, v120
	v_add_f32_e32 v120, v55, v120
	v_add_f32_e32 v120, v56, v120
	v_add_f32_e32 v120, v57, v120
	v_cvt_pk_bf16_f32 v136, v52, v53
	v_cvt_pk_bf16_f32 v137, v54, v55
	s_waitcnt lgkmcnt(14)
	v_mfma_f32_32x32x16_bf16 v[64:79], v[170:173], v[150:153], v[64:79]
	ds_read_b64_tr_b16 v[52:53], v189 offset:27648
	ds_read_b64_tr_b16 v[54:55], v189 offset:28160
	v_add_f32_e32 v120, v58, v120
	v_add_f32_e32 v120, v59, v120
	v_add_f32_e32 v120, v60, v120
	v_add_f32_e32 v120, v61, v120
	v_cvt_pk_bf16_f32 v130, v56, v57
	v_cvt_pk_bf16_f32 v131, v58, v59
	s_waitcnt lgkmcnt(14)
	v_mfma_f32_32x32x16_bf16 v[96:111], v[174:177], v[146:149], v[96:111]
	ds_read_b64_tr_b16 v[56:57], v189 offset:31744
	ds_read_b64_tr_b16 v[58:59], v189 offset:32256
	v_mfma_f32_32x32x16_bf16 v[64:79], v[80:83], v[146:149], v[64:79]
	v_add_f32_e32 v80, v62, v120
	v_add_f32_e32 v80, v63, v80
	v_add_f32_e32 v80, 0, v80
	v_cvt_pk_bf16_f32 v132, v60, v61
	v_cvt_pk_bf16_f32 v133, v62, v63
	s_add_u32 s10, s8, 0xba0000
	s_addc_u32 s11, s9, 0
	s_add_i32 s17, s17, 0xa000
	s_mov_b32 s18, m0
	s_mov_b32 m0, s17
	s_nop 0
	global_load_lds_dwordx4 v185, s[10:11]
	s_mov_b32 m0, s18
	v_add_f32_e32 v128, v178, v80
	s_waitcnt lgkmcnt(14)
	v_mfma_f32_32x32x16_bf16 v[0:15], v[142:145], v[84:87], v[0:15]
	v_exp_f32_e32 v96, v96
	v_exp_f32_e32 v97, v97
	v_exp_f32_e32 v98, v98
	v_exp_f32_e32 v99, v99
	s_waitcnt lgkmcnt(12)
	v_mfma_f32_32x32x16_bf16 v[16:31], v[142:145], v[112:115], v[16:31]
	v_exp_f32_e32 v100, v100
	v_exp_f32_e32 v101, v101
	v_exp_f32_e32 v102, v102
	v_exp_f32_e32 v103, v103
	ds_read_b128 v[60:63], v187 offset:16384
	ds_read_b128 v[120:123], v187 offset:16896
	s_waitcnt lgkmcnt(12)
	v_mfma_f32_32x32x16_bf16 v[0:15], v[138:141], v[88:91], v[0:15]
	v_exp_f32_e32 v104, v104
	v_exp_f32_e32 v105, v105
	v_exp_f32_e32 v106, v106
	v_exp_f32_e32 v107, v107
	ds_read_b128 v[124:127], v187 offset:18432
	ds_read_b128 v[162:165], v187 offset:18944
	s_waitcnt lgkmcnt(12)
	v_mfma_f32_32x32x16_bf16 v[16:31], v[138:141], v[92:95], v[16:31]
	v_exp_f32_e32 v108, v108
	v_exp_f32_e32 v109, v109
	v_exp_f32_e32 v110, v110
	v_exp_f32_e32 v111, v111
	ds_read_b128 v[166:169], v187 offset:20480
	ds_read_b128 v[170:173], v187 offset:20992
	s_waitcnt lgkmcnt(12)
	v_mfma_f32_32x32x16_bf16 v[0:15], v[134:137], v[116:119], v[0:15]
	v_exp_f32_e32 v64, v64
	v_exp_f32_e32 v65, v65
	v_exp_f32_e32 v66, v66
	v_exp_f32_e32 v67, v67
	ds_read_b128 v[116:119], v187 offset:22528
	ds_read_b128 v[112:115], v187 offset:23040
	s_waitcnt lgkmcnt(12)
	v_mfma_f32_32x32x16_bf16 v[16:31], v[134:137], v[48:51], v[16:31]
	v_exp_f32_e32 v68, v68
	v_exp_f32_e32 v69, v69
	v_exp_f32_e32 v70, v70
	v_exp_f32_e32 v71, v71
	s_waitcnt lgkmcnt(10)
	v_mfma_f32_32x32x16_bf16 v[0:15], v[130:133], v[52:55], v[0:15]
	v_exp_f32_e32 v72, v72
	v_exp_f32_e32 v73, v73
	v_exp_f32_e32 v74, v74
	v_exp_f32_e32 v75, v75
	s_waitcnt lgkmcnt(8)
	v_mfma_f32_32x32x16_bf16 v[16:31], v[130:133], v[56:59], v[16:31]
	v_exp_f32_e32 v76, v76
	v_exp_f32_e32 v77, v77
	v_exp_f32_e32 v78, v78
	v_exp_f32_e32 v79, v79
	s_waitcnt vmcnt(1) lgkmcnt(0)
	s_barrier
;   #define RESC() do { if constexpr (!NOMAX) if (resc) { asm volatile("s_waitcnt lgkmcnt(0)" ::: "memory"); \
;       _Pragma("unroll") for (int d_ = 0; d_ < 2 * DV2; ++d_) _Pragma("unroll") for (int r = 0; r < 16; ++r) o[d_][r] *= wsf[crow(r, hi)]; } } while (0)
;   #define ROT() do { sl_prev = sl_cur; sl_cur = sl_next; sl_next = (sl_next == (NSLOT - 1) * SLOTB) ? 0 : sl_next + SLOTB; } while (0)
;   #define ENDW(tt) do { if constexpr (DV2 == 2) { if ((tt) + 3 < NT) { WAIT_BAR(3); } else if ((tt) + 2 < NT) { WAIT_BAR(2); } else { WAIT_BAR(0); } } \
;     else { if ((tt) + 3 < NT) { WAIT_BAR(2); } else if ((tt) + 2 < NT) { WAIT_BAR(1); } else { WAIT_BAR(0); } } } while (0)
;     ...
;   for (; t + 1 < NT; t += 2) {
;     STEP(pB0, pB1, pA0, pA1, t, (t + 3 < NT), (t + 1 < NT), (t + 1 < NT));         ENDW(t);     RESC(); ROT();
;     STEP(pA0, pA1, pB0, pB1, t + 1, (t + 4 < NT), (t + 2 < NT), (t + 2 < NT));     ENDW(t + 1); RESC(); ROT();
	ds_read_b64_tr_b16 v[174:175], v189 offset:32768
	ds_read_b64_tr_b16 v[176:177], v189 offset:33280
	v_add_f32_e32 v48, v96, v97
	v_add_f32_e32 v48, v98, v48
	v_add_f32_e32 v48, v99, v48
	v_add_f32_e32 v48, v100, v48
	v_add_f32_e32 v48, v101, v48
	v_cvt_pk_bf16_f32 v142, v96, v97
	v_cvt_pk_bf16_f32 v143, v98, v99
	s_waitcnt lgkmcnt(9)
	v_mfma_f32_32x32x16_bf16 v[80:95], v[60:63], v[158:161], v[32:47]
	ds_read_b64_tr_b16 v[96:97], v189 offset:36864
	ds_read_b64_tr_b16 v[98:99], v189 offset:37376
	v_add_f32_e32 v48, v102, v48
	v_add_f32_e32 v48, v103, v48
	v_add_f32_e32 v48, v104, v48
	v_add_f32_e32 v129, v105, v48
	s_waitcnt lgkmcnt(10)
	v_mfma_f32_32x32x16_bf16 v[48:63], v[120:123], v[158:161], v[32:47]
	v_cvt_pk_bf16_f32 v144, v100, v101
	v_cvt_pk_bf16_f32 v145, v102, v103
	ds_read_b64_tr_b16 v[100:101], v189 offset:33792
	ds_read_b64_tr_b16 v[102:103], v189 offset:34304
	v_add_f32_e32 v120, v106, v129
	v_add_f32_e32 v120, v107, v120
	v_add_f32_e32 v120, v108, v120
	v_add_f32_e32 v120, v109, v120
	v_cvt_pk_bf16_f32 v138, v104, v105
	v_cvt_pk_bf16_f32 v139, v106, v107
	s_waitcnt lgkmcnt(11)
	v_mfma_f32_32x32x16_bf16 v[80:95], v[124:127], v[154:157], v[80:95]
	ds_read_b64_tr_b16 v[104:105], v189 offset:37888
	ds_read_b64_tr_b16 v[106:107], v189 offset:38400
	s_waitcnt lgkmcnt(12)
	v_mfma_f32_32x32x16_bf16 v[48:63], v[162:165], v[154:157], v[48:63]
	v_add_f32_e32 v120, v110, v120
	v_add_f32_e32 v120, v111, v120
	v_add_f32_e32 v120, v64, v120
	v_add_f32_e32 v124, v65, v120
	v_cvt_pk_bf16_f32 v140, v108, v109
	v_cvt_pk_bf16_f32 v141, v110, v111
	ds_read_b64_tr_b16 v[120:121], v189 offset:34816
	ds_read_b64_tr_b16 v[122:123], v189 offset:35328
	v_add_f32_e32 v108, v66, v124
	v_add_f32_e32 v108, v67, v108
	v_add_f32_e32 v108, v68, v108
	v_add_f32_e32 v108, v69, v108
	v_cvt_pk_bf16_f32 v134, v64, v65
	v_cvt_pk_bf16_f32 v135, v66, v67
	s_waitcnt lgkmcnt(13)
	v_mfma_f32_32x32x16_bf16 v[80:95], v[166:169], v[150:153], v[80:95]
	ds_read_b64_tr_b16 v[64:65], v189 offset:38912
	ds_read_b64_tr_b16 v[66:67], v189 offset:39424
	s_waitcnt lgkmcnt(14)
	v_mfma_f32_32x32x16_bf16 v[48:63], v[170:173], v[150:153], v[48:63]
	v_add_f32_e32 v108, v70, v108
	v_add_f32_e32 v108, v71, v108
	v_add_f32_e32 v108, v72, v108
	v_add_f32_e32 v108, v73, v108
	v_cvt_pk_bf16_f32 v136, v68, v69
	v_cvt_pk_bf16_f32 v137, v70, v71
	ds_read_b64_tr_b16 v[68:69], v189 offset:35840
	ds_read_b64_tr_b16 v[70:71], v189 offset:36352
	v_add_f32_e32 v108, v74, v108
	v_add_f32_e32 v108, v75, v108
	v_add_f32_e32 v108, v76, v108
	v_add_f32_e32 v108, v77, v108
	v_cvt_pk_bf16_f32 v130, v72, v73
	v_cvt_pk_bf16_f32 v131, v74, v75
	s_waitcnt lgkmcnt(14)
	v_mfma_f32_32x32x16_bf16 v[80:95], v[116:119], v[146:149], v[80:95]
	ds_read_b64_tr_b16 v[72:73], v189 offset:39936
	ds_read_b64_tr_b16 v[74:75], v189 offset:40448
	v_mfma_f32_32x32x16_bf16 v[48:63], v[112:115], v[146:149], v[48:63]
	v_add_f32_e32 v108, v78, v108
	v_add_f32_e32 v108, v79, v108
	v_add_f32_e32 v108, 0, v108
	v_cvt_pk_bf16_f32 v132, v76, v77
	v_cvt_pk_bf16_f32 v133, v78, v79
	s_add_u32 s8, s8, 0xbd0000
	s_addc_u32 s9, s9, 0
	s_mov_b32 s10, m0
	s_mov_b32 m0, s15
	s_nop 0
	global_load_lds_dwordx4 v185, s[8:9]
	s_mov_b32 m0, s10
	v_add_f32_e32 v108, v128, v108
	s_waitcnt lgkmcnt(14)
	v_mfma_f32_32x32x16_bf16 v[0:15], v[142:145], v[174:177], v[0:15]
	v_exp_f32_e32 v80, v80
	v_exp_f32_e32 v81, v81
	v_exp_f32_e32 v82, v82
	v_exp_f32_e32 v83, v83
	s_waitcnt lgkmcnt(12)
	v_mfma_f32_32x32x16_bf16 v[16:31], v[142:145], v[96:99], v[16:31]
	v_exp_f32_e32 v84, v84
	v_exp_f32_e32 v85, v85
	v_exp_f32_e32 v86, v86
	v_exp_f32_e32 v87, v87
	ds_read_b128 v[110:113], v187
	ds_read_b128 v[114:117], v187 offset:512
	s_waitcnt lgkmcnt(12)
	v_mfma_f32_32x32x16_bf16 v[0:15], v[138:141], v[100:103], v[0:15]
	v_exp_f32_e32 v88, v88
	v_exp_f32_e32 v89, v89
	v_exp_f32_e32 v90, v90
	v_exp_f32_e32 v91, v91
	ds_read_b128 v[124:127], v187 offset:2048
	ds_read_b128 v[162:165], v187 offset:2560
	s_waitcnt lgkmcnt(12)
	v_mfma_f32_32x32x16_bf16 v[16:31], v[138:141], v[104:107], v[16:31]
	v_exp_f32_e32 v92, v92
	v_exp_f32_e32 v93, v93
	v_exp_f32_e32 v94, v94
	v_exp_f32_e32 v95, v95
	ds_read_b128 v[166:169], v187 offset:4096
	ds_read_b128 v[170:173], v187 offset:4608
	s_waitcnt lgkmcnt(12)
	v_mfma_f32_32x32x16_bf16 v[0:15], v[134:137], v[120:123], v[0:15]
	v_exp_f32_e32 v48, v48
	v_exp_f32_e32 v49, v49
	v_exp_f32_e32 v50, v50
	v_exp_f32_e32 v51, v51
	ds_read_b128 v[118:121], v187 offset:6144
	ds_read_b128 v[104:107], v187 offset:6656
	s_waitcnt lgkmcnt(12)
	v_mfma_f32_32x32x16_bf16 v[16:31], v[134:137], v[64:67], v[16:31]
	v_exp_f32_e32 v52, v52
	v_exp_f32_e32 v53, v53
	v_exp_f32_e32 v54, v54
	v_exp_f32_e32 v55, v55
	s_waitcnt lgkmcnt(10)
	v_mfma_f32_32x32x16_bf16 v[0:15], v[130:133], v[68:71], v[0:15]
	v_exp_f32_e32 v56, v56
	v_exp_f32_e32 v57, v57
	v_exp_f32_e32 v58, v58
	v_exp_f32_e32 v59, v59
	s_waitcnt lgkmcnt(8)
	v_mfma_f32_32x32x16_bf16 v[16:31], v[130:133], v[72:75], v[16:31]
	v_exp_f32_e32 v60, v60
	v_exp_f32_e32 v61, v61
	v_exp_f32_e32 v62, v62
	v_exp_f32_e32 v63, v63
	s_waitcnt vmcnt(0) lgkmcnt(0)
	s_barrier
;   #define RESC() do { if constexpr (!NOMAX) if (resc) { asm volatile("s_waitcnt lgkmcnt(0)" ::: "memory"); \
;       _Pragma("unroll") for (int d_ = 0; d_ < 2 * DV2; ++d_) _Pragma("unroll") for (int r = 0; r < 16; ++r) o[d_][r] *= wsf[crow(r, hi)]; } } while (0)
;     ...
;   STEP(pB0, pB1, pA0, pA1, NT - 1, false, false, false); RESC();
	ds_read_b64_tr_b16 v[96:97], v189 offset:40960
	ds_read_b64_tr_b16 v[98:99], v189 offset:41472
	v_add_f32_e32 v64, v80, v81
	v_add_f32_e32 v64, v82, v64
	v_add_f32_e32 v64, v83, v64
	v_add_f32_e32 v64, v84, v64
	v_add_f32_e32 v100, v85, v64
	v_cvt_pk_bf16_f32 v142, v80, v81
	v_cvt_pk_bf16_f32 v143, v82, v83
	s_waitcnt lgkmcnt(9)
	v_mfma_f32_32x32x16_bf16 v[64:79], v[110:113], v[158:161], v[32:47]
	ds_read_b64_tr_b16 v[80:81], v189 offset:45056
	ds_read_b64_tr_b16 v[82:83], v189 offset:45568
	s_waitcnt lgkmcnt(10)
	v_mfma_f32_32x32x16_bf16 v[32:47], v[114:117], v[158:161], v[32:47]
	v_add_f32_e32 v100, v86, v100
	v_add_f32_e32 v100, v87, v100
	v_add_f32_e32 v100, v88, v100
	v_add_f32_e32 v109, v89, v100
	v_cvt_pk_bf16_f32 v144, v84, v85
	v_cvt_pk_bf16_f32 v145, v86, v87
	ds_read_b64_tr_b16 v[100:101], v189 offset:41984
	ds_read_b64_tr_b16 v[102:103], v189 offset:42496
	v_add_f32_e32 v84, v90, v109
	v_add_f32_e32 v84, v91, v84
	v_add_f32_e32 v84, v92, v84
	v_add_f32_e32 v109, v93, v84
	v_cvt_pk_bf16_f32 v138, v88, v89
	v_cvt_pk_bf16_f32 v139, v90, v91
	s_waitcnt lgkmcnt(11)
	v_mfma_f32_32x32x16_bf16 v[64:79], v[124:127], v[154:157], v[64:79]
	ds_read_b64_tr_b16 v[84:85], v189 offset:46080
	ds_read_b64_tr_b16 v[86:87], v189 offset:46592
	s_waitcnt lgkmcnt(12)
	v_mfma_f32_32x32x16_bf16 v[32:47], v[162:165], v[154:157], v[32:47]
	v_add_f32_e32 v88, v94, v109
	v_add_f32_e32 v88, v95, v88
	v_add_f32_e32 v88, v48, v88
	v_add_f32_e32 v109, v49, v88
	v_cvt_pk_bf16_f32 v140, v92, v93
	v_cvt_pk_bf16_f32 v141, v94, v95
	ds_read_b64_tr_b16 v[88:89], v189 offset:43008
	ds_read_b64_tr_b16 v[90:91], v189 offset:43520
	v_add_f32_e32 v92, v50, v109
	v_add_f32_e32 v92, v51, v92
	v_add_f32_e32 v92, v52, v92
	v_add_f32_e32 v92, v53, v92
	v_cvt_pk_bf16_f32 v134, v48, v49
	v_cvt_pk_bf16_f32 v135, v50, v51
	s_waitcnt lgkmcnt(13)
	v_mfma_f32_32x32x16_bf16 v[64:79], v[166:169], v[150:153], v[64:79]
	ds_read_b64_tr_b16 v[48:49], v189 offset:47104
	ds_read_b64_tr_b16 v[50:51], v189 offset:47616
	s_waitcnt lgkmcnt(14)
	v_mfma_f32_32x32x16_bf16 v[32:47], v[170:173], v[150:153], v[32:47]
	v_add_f32_e32 v92, v54, v92
	v_add_f32_e32 v92, v55, v92
	v_add_f32_e32 v92, v56, v92
	v_add_f32_e32 v109, v57, v92
	v_cvt_pk_bf16_f32 v136, v52, v53
	v_cvt_pk_bf16_f32 v137, v54, v55
	ds_read_b64_tr_b16 v[92:93], v189 offset:44032
	ds_read_b64_tr_b16 v[94:95], v189 offset:44544
	v_add_f32_e32 v52, v58, v109
	v_add_f32_e32 v52, v59, v52
	v_add_f32_e32 v52, v60, v52
	v_add_f32_e32 v109, v61, v52
	v_cvt_pk_bf16_f32 v130, v56, v57
	v_cvt_pk_bf16_f32 v131, v58, v59
	s_waitcnt lgkmcnt(14)
	v_mfma_f32_32x32x16_bf16 v[64:79], v[118:121], v[146:149], v[64:79]
	ds_read_b64_tr_b16 v[52:53], v189 offset:48128
	ds_read_b64_tr_b16 v[54:55], v189 offset:48640
	v_mfma_f32_32x32x16_bf16 v[32:47], v[104:107], v[146:149], v[32:47]
	v_add_f32_e32 v56, v62, v109
	v_add_f32_e32 v56, v63, v56
	v_add_f32_e32 v56, 0, v56
	v_cvt_pk_bf16_f32 v132, v60, v61
	v_cvt_pk_bf16_f32 v133, v62, v63
	s_nop 3
	v_exp_f32_e32 v64, v64
	v_exp_f32_e32 v65, v65
	v_exp_f32_e32 v66, v66
	v_exp_f32_e32 v67, v67
	s_nop 0
	v_exp_f32_e32 v68, v68
	v_exp_f32_e32 v69, v69
	v_exp_f32_e32 v70, v70
	v_exp_f32_e32 v71, v71
	s_nop 0
	v_exp_f32_e32 v72, v72
	v_exp_f32_e32 v73, v73
	v_exp_f32_e32 v74, v74
	v_exp_f32_e32 v75, v75
	s_nop 0
	v_exp_f32_e32 v76, v76
	v_exp_f32_e32 v77, v77
	v_exp_f32_e32 v78, v78
	v_exp_f32_e32 v79, v79
	v_exp_f32_e32 v32, v32
	v_exp_f32_e32 v33, v33
	v_exp_f32_e32 v34, v34
	v_exp_f32_e32 v35, v35
	s_nop 0
	v_exp_f32_e32 v36, v36
	v_exp_f32_e32 v37, v37
	v_exp_f32_e32 v38, v38
	v_exp_f32_e32 v39, v39
	s_nop 0
	v_exp_f32_e32 v40, v40
	v_exp_f32_e32 v41, v41
	v_exp_f32_e32 v42, v42
	v_exp_f32_e32 v43, v43
	s_nop 0
	v_exp_f32_e32 v44, v44
	v_exp_f32_e32 v45, v45
	v_exp_f32_e32 v46, v46
	v_exp_f32_e32 v47, v47
	s_waitcnt lgkmcnt(14)
; #define SBAR() __builtin_amdgcn_sched_barrier(0)
;   #define PKW(P, B) cvtpk_s(P[B], P[B + 1])
;     ...
;   { float sacc = pB0[0] + pB0[1]; _Pragma("unroll") for (int r = 2; r < 16; ++r) sacc += pB0[r]; _Pragma("unroll") for (int r = 0; r < 16; ++r) sacc += pB1[r]; l_reg += sacc;
;     pw0 = (u32x4){PKW(pB0, 0), PKW(pB0, 2), PKW(pB0, 4), PKW(pB0, 6)}; pw1 = (u32x4){PKW(pB0, 8), PKW(pB0, 10), PKW(pB0, 12), PKW(pB0, 14)}; pw2 = (u32x4){PKW(pB1, 0), PKW(pB1, 2), PKW(pB1, 4), PKW(pB1, 6)}; pw3 = (u32x4){PKW(pB1, 8), PKW(pB1, 10), PKW(pB1, 12), PKW(pB1, 14)};
;     SBAR(); pv(o, vb0 + DV2 * sl_cur, PAF(0), PAF(1), PAF(2), PAF(3)); if constexpr (DV2 == 2) pv(o + 2, vb0 + DV2 * sl_cur + 8192, PAF(0), PAF(1), PAF(2), PAF(3)); }
;     ...
;   { auto rr = __builtin_amdgcn_permlane32_swap(__float_as_uint(l_reg), __float_as_uint(l_reg), false, false); l_reg = __uint_as_float(rr[0]) + __uint_as_float(rr[1]); }
;   int lane_e; asm volatile("v_mbcnt_lo_u32_b32 %0, -1, 0\n\tv_mbcnt_hi_u32_b32 %0, -1, %0" : "=v"(lane_e));
;   const int r32e = lane_e & 31, hie = lane_e >> 5;
;   if (hie == 0) wsf[32 + r32e] = l_reg; asm volatile("s_waitcnt lgkmcnt(0)" ::: "memory");
	v_mfma_f32_32x32x16_bf16 v[0:15], v[142:145], v[96:99], v[0:15]
	v_add_f32_e32 v57, v64, v65
	v_add_f32_e32 v57, v66, v57
	v_add_f32_e32 v57, v67, v57
	v_add_f32_e32 v57, v68, v57
	v_add_f32_e32 v57, v69, v57
	v_add_f32_e32 v57, v70, v57
	v_add_f32_e32 v57, v71, v57
	s_waitcnt lgkmcnt(12)
	v_mfma_f32_32x32x16_bf16 v[16:31], v[142:145], v[80:83], v[16:31]
	v_add_f32_e32 v57, v72, v57
	v_add_f32_e32 v57, v73, v57
	v_add_f32_e32 v57, v74, v57
	v_add_f32_e32 v57, v75, v57
	v_add_f32_e32 v57, v76, v57
	v_add_f32_e32 v57, v77, v57
	v_add_f32_e32 v57, v78, v57
	s_waitcnt lgkmcnt(10)
	v_mfma_f32_32x32x16_bf16 v[0:15], v[138:141], v[100:103], v[0:15]
	v_add_f32_e32 v57, v79, v57
	v_add_f32_e32 v57, v32, v57
	v_add_f32_e32 v57, v33, v57
	v_add_f32_e32 v57, v34, v57
	v_add_f32_e32 v57, v35, v57
	v_add_f32_e32 v57, v36, v57
	v_add_f32_e32 v57, v37, v57
	s_waitcnt lgkmcnt(8)
	v_mfma_f32_32x32x16_bf16 v[16:31], v[138:141], v[84:87], v[16:31]
	v_add_f32_e32 v57, v38, v57
	v_add_f32_e32 v57, v39, v57
	v_add_f32_e32 v57, v40, v57
	v_add_f32_e32 v57, v41, v57
	v_add_f32_e32 v57, v42, v57
	v_add_f32_e32 v57, v43, v57
	v_add_f32_e32 v57, v44, v57
	s_waitcnt lgkmcnt(6)
	v_mfma_f32_32x32x16_bf16 v[0:15], v[134:137], v[88:91], v[0:15]
	v_add_f32_e32 v57, v45, v57
	v_add_f32_e32 v57, v46, v57
	v_add_f32_e32 v57, v47, v57
	v_add_f32_e32 v56, v108, v56
	v_add_f32_e32 v56, v56, v57
	v_cvt_pk_bf16_f32 v32, v32, v33
	v_cvt_pk_bf16_f32 v33, v34, v35
	s_waitcnt lgkmcnt(4)
	v_mfma_f32_32x32x16_bf16 v[16:31], v[134:137], v[48:51], v[16:31]
	v_cvt_pk_bf16_f32 v58, v64, v65
	v_cvt_pk_bf16_f32 v59, v66, v67
	v_cvt_pk_bf16_f32 v60, v68, v69
	v_cvt_pk_bf16_f32 v61, v70, v71
	v_cvt_pk_bf16_f32 v62, v72, v73
	v_cvt_pk_bf16_f32 v63, v74, v75
	v_cvt_pk_bf16_f32 v64, v76, v77
	s_waitcnt lgkmcnt(2)
	v_mfma_f32_32x32x16_bf16 v[0:15], v[130:133], v[92:95], v[0:15]
	v_cvt_pk_bf16_f32 v65, v78, v79
	v_cvt_pk_bf16_f32 v34, v36, v37
	v_cvt_pk_bf16_f32 v35, v38, v39
	v_cvt_pk_bf16_f32 v36, v40, v41
	v_cvt_pk_bf16_f32 v37, v42, v43
	v_cvt_pk_bf16_f32 v38, v44, v45
	v_cvt_pk_bf16_f32 v39, v46, v47
	s_waitcnt lgkmcnt(0)
	v_mfma_f32_32x32x16_bf16 v[16:31], v[130:133], v[52:55], v[16:31]
	ds_read_b64_tr_b16 v[40:41],v188 offset:0
	ds_read_b64_tr_b16 v[42:43],v188 offset:512
	ds_read_b64_tr_b16 v[44:45],v188 offset:1024
	ds_read_b64_tr_b16 v[46:47],v188 offset:1536
	ds_read_b64_tr_b16 v[48:49],v188 offset:2048
	ds_read_b64_tr_b16 v[50:51],v188 offset:2560
	ds_read_b64_tr_b16 v[52:53],v188 offset:3072
	ds_read_b64_tr_b16 v[54:55],v188 offset:3584
	s_waitcnt lgkmcnt(0)
	s_nop 0
	v_mfma_f32_32x32x16_bf16 v[0:15], v[58:61], v[40:43], v[0:15]
	ds_read_b64_tr_b16 v[40:41],v188 offset:4096
	ds_read_b64_tr_b16 v[42:43],v188 offset:4608
	v_mfma_f32_32x32x16_bf16 v[0:15], v[62:65], v[44:47], v[0:15]
	ds_read_b64_tr_b16 v[44:45],v188 offset:5120
	ds_read_b64_tr_b16 v[46:47],v188 offset:5632
	v_mfma_f32_32x32x16_bf16 v[0:15], v[32:35], v[48:51], v[0:15]
	ds_read_b64_tr_b16 v[48:49],v188 offset:6144
	ds_read_b64_tr_b16 v[50:51],v188 offset:6656
	v_mfma_f32_32x32x16_bf16 v[0:15], v[36:39], v[52:55], v[0:15]
	ds_read_b64_tr_b16 v[52:53],v188 offset:7168
	ds_read_b64_tr_b16 v[54:55],v188 offset:7680
	s_waitcnt lgkmcnt(0)
	v_mfma_f32_32x32x16_bf16 v[16:31], v[58:61], v[40:43], v[16:31]
	v_mfma_f32_32x32x16_bf16 v[16:31], v[62:65], v[44:47], v[16:31]
	v_mfma_f32_32x32x16_bf16 v[16:31], v[32:35], v[48:51], v[16:31]
	v_mov_b32_e32 v33, v56
	s_nop 1
	v_permlane32_swap_b32_e32 v56, v33
	v_mbcnt_lo_u32_b32 v32, -1, 0
	v_mbcnt_hi_u32_b32 v32, -1, v32
	s_nop 0
	v_cmp_gt_u32_e32 vcc, 32, v32
	v_mfma_f32_32x32x16_bf16 v[16:31], v[36:39], v[52:55], v[16:31]
	s_and_saveexec_b64 s[8:9], vcc
	s_cbranch_execz .LBB0_968
	v_add_f32_e32 v33, v56, v33
	v_lshl_add_u32 v34, v32, 2, s16
	ds_write_b32 v34, v33 offset:49280
	s_branch .LBB0_968
